# EpiBf epilogue: second batch of SSQ/SSK loads issued under the first (one exposed latency instead of two)
# baseline (speedup 1.0000x reference)
.LBB0_529:
	s_or_b64 exec, exec, s[8:9]
	s_lshl_b32 s7, s20, 8
	v_add3_u32 v206, s7, v235, v114
	v_add_u32_e32 v190, 0xb0, v206
	v_ashrrev_i32_e32 v207, 31, v206
	v_readlane_b32 s8, v253, 56
	v_add_u32_e32 v202, 16, v206
	v_ashrrev_i32_e32 v191, 31, v190
	v_lshlrev_b64 v[154:155], 4, v[206:207]
	v_readlane_b32 s9, v253, 57
	v_ashrrev_i32_e32 v203, 31, v202
	v_lshlrev_b64 v[242:243], 4, v[190:191]
	v_lshl_add_u64 v[114:115], s[8:9], 0, v[154:155]
	v_lshlrev_b64 v[156:157], 4, v[202:203]
	v_lshl_add_u64 v[118:119], s[8:9], 0, v[242:243]
	global_load_dwordx4 v[138:141], v[114:115], off
	v_add_u32_e32 v200, 32, v206
	global_load_dwordx4 v[118:121], v[118:119], off
	v_lshl_add_u64 v[114:115], s[8:9], 0, v[156:157]
	global_load_dwordx4 v[142:145], v[114:115], off
	v_ashrrev_i32_e32 v201, 31, v200
	v_add_u32_e32 v198, 48, v206
	v_readlane_b32 s10, v253, 58
	v_lshlrev_b64 v[158:159], 4, v[200:201]
	v_ashrrev_i32_e32 v199, 31, v198
	v_mov_b64_e32 v[208:209], s[92:93]
	v_readlane_b32 s11, v253, 59
	v_lshl_add_u64 v[114:115], s[8:9], 0, v[158:159]
	v_lshlrev_b64 v[160:161], 4, v[198:199]
	global_load_dwordx4 v[162:165], v[114:115], off
	v_add_u32_e32 v196, 0x80, v206
	v_ashrrev_i32_e32 v197, 31, v196
	v_add_u32_e32 v194, 0x90, v206
	v_lshlrev_b64 v[222:223], 4, v[196:197]
	v_ashrrev_i32_e32 v195, 31, v194
	v_add_u32_e32 v192, 0xa0, v206
	v_lshlrev_b64 v[230:231], 4, v[194:195]
	v_ashrrev_i32_e32 v193, 31, v192
	v_lshlrev_b64 v[232:233], 4, v[192:193]
	v_lshl_add_u64 v[246:247], s[10:11], 0, v[154:155]
	global_load_dwordx4 v[212:215], v[246:247], off
	v_lshl_add_u64 v[248:249], s[8:9], 0, v[160:161]
	v_lshl_add_u64 v[246:247], s[10:11], 0, v[156:157]
	global_load_dwordx4 v[166:169], v[248:249], off
	global_load_dwordx4 v[216:219], v[246:247], off
	v_lshl_add_u64 v[248:249], s[8:9], 0, v[222:223]
	v_lshl_add_u64 v[246:247], s[10:11], 0, v[158:159]
	global_load_dwordx4 v[146:149], v[248:249], off
	global_load_dwordx4 v[170:173], v[246:247], off
	v_lshl_add_u64 v[248:249], s[8:9], 0, v[230:231]
	v_lshl_add_u64 v[246:247], s[10:11], 0, v[160:161]
	global_load_dwordx4 v[150:153], v[248:249], off
	global_load_dwordx4 v[174:177], v[246:247], off
	v_lshl_add_u64 v[248:249], s[8:9], 0, v[232:233]
	v_lshl_add_u64 v[246:247], s[10:11], 0, v[222:223]
	global_load_dwordx4 v[114:117], v[248:249], off
	global_load_dwordx4 v[154:157], v[246:247], off
	v_lshl_add_u64 v[246:247], s[10:11], 0, v[230:231]
	global_load_dwordx4 v[158:161], v[246:247], off
	s_waitcnt vmcnt(10)
	v_mov_b32_e32 v251, v138
	v_mov_b32_e32 v250, v142
	v_mov_b32_e32 v138, v143
	v_pk_add_f32 v[138:139], v[250:251], v[138:139]
	v_mov_b32_e32 v142, v144
	v_mov_b32_e32 v143, v140
	v_pk_add_f32 v[138:139], v[142:143], v[138:139]
	v_mov_b32_e32 v140, v145
	v_pk_add_f32 v[138:139], v[140:141], v[138:139]
	v_lshl_add_u64 v[142:143], s[10:11], 0, v[242:243]
	v_pk_fma_f32 v[204:205], v[138:139], s[58:59], v[208:209] op_sel_hi:[1,0,0]
	v_cmp_gt_f32_e32 vcc, s93, v204
	v_cmp_gt_f32_e64 s[8:9], s93, v205
	global_load_dwordx4 v[142:145], v[142:143], off
	v_lshl_add_u64 v[138:139], s[10:11], 0, v[232:233]
	global_load_dwordx4 v[138:141], v[138:139], off
	s_waitcnt vmcnt(0)
	v_mov_b32_e32 v223, v212
	v_mov_b32_e32 v222, v216
	v_mov_b32_e32 v212, v217
	v_pk_add_f32 v[212:213], v[222:223], v[212:213]
	v_mov_b32_e32 v216, v218
	v_mov_b32_e32 v217, v214
	v_pk_add_f32 v[212:213], v[216:217], v[212:213]
	v_mov_b32_e32 v214, v219
	v_pk_add_f32 v[212:213], v[214:215], v[212:213]
	s_nop 0
	v_pk_fma_f32 v[208:209], v[212:213], s[64:65], v[208:209] op_sel_hi:[1,0,0]
	s_nop 0
	v_mul_f32_e32 v189, 0x4b800000, v209
	v_cmp_gt_f32_e64 s[12:13], s93, v209
	v_cmp_gt_f32_e64 s[10:11], s93, v208
	s_nop 0
	v_cndmask_b32_e64 v189, v209, v189, s[12:13]
	v_rsq_f32_e32 v189, v189
	s_nop 0
	v_mul_f32_e32 v209, 0x45800000, v189
	v_cndmask_b32_e64 v209, v189, v209, s[12:13]
	v_cmp_lt_i32_e64 s[12:13], 0, v240
	s_and_saveexec_b64 s[18:19], s[12:13]
	s_xor_b64 s[18:19], exec, s[18:19]
	s_cbranch_execz .LBB0_533
	v_cmp_eq_u32_e64 s[12:13], 1, v240
	v_mov_b32_e32 v212, 1.0
	s_and_saveexec_b64 s[20:21], s[12:13]
	v_mov_b32_e32 v212, v209
	s_or_b64 exec, exec, s[20:21]
